# P2b: copies rewritten (all loads in flight), s5_sample items moved off the lru_unit<2> workgroups, P5 tail-row loads batched
# speedup vs baseline: 1.1606x; 1.0120x over previous
.LBB0_535:
	v_readlane_b32 s0, v250, 0
	s_lshl_b32 s15, s0, 3
	s_mov_b32 s65, s94
	s_mov_b32 s66, s15
	s_cmpk_lt_i32 s94, 0x80
	s_cbranch_scc1 .Ls5s_nobal
	s_sub_i32 s65, s94, 64
	s_cmp_ge_i32 s0, s65
	s_cselect_b32 s66, 0x1000, s15
.Ls5s_nobal:
	s_lshl_b32 s65, s65, 3
	v_ashrrev_i32_e32 v2, 6, v34
	v_add_u32_e32 v3, s66, v2
	s_movk_i32 s0, 0x1000
	v_readlane_b32 s1, v250, 1
	s_lshl_b32 s64, s94, 3
	v_cmp_gt_i32_e32 vcc, s0, v3
	v_mbcnt_lo_u32_b32 v225, -1, 0
	s_and_saveexec_b64 s[0:1], vcc
	v_readlane_b32 s18, v249, 5
	v_readlane_b32 s30, v248, 3
	v_readlane_b32 s34, v248, 7
	v_readlane_b32 s19, v249, 6
	v_readlane_b32 s31, v248, 4
	v_readlane_b32 s35, v248, 8
	s_cbranch_execz .LBB0_540
	v_mbcnt_hi_u32_b32 v4, -1, v225
	v_and_b32_e32 v7, 64, v4
	v_xor_b32_e32 v6, 32, v4
	v_add_u32_e32 v8, 64, v7
	v_cmp_lt_i32_e32 vcc, v6, v8
	s_add_u32 s24, s90, 0x30a0000
	v_and_b32_e32 v2, 63, v34
	v_cndmask_b32_e32 v6, v4, v6, vcc
	v_lshlrev_b32_e32 v7, 2, v6
	v_and_b32_e32 v6, 16, v34
	v_cmp_eq_u32_e64 s[40:41], 0, v6
	v_xor_b32_e32 v6, 16, v4
	v_cmp_lt_i32_e32 vcc, v6, v8
	s_addc_u32 s25, s91, 0
	v_mov_b32_e32 v5, 0
	v_cndmask_b32_e32 v6, v4, v6, vcc
	v_lshlrev_b32_e32 v16, 2, v6
	v_and_b32_e32 v6, 8, v34
	v_cmp_eq_u32_e64 s[42:43], 0, v6
	v_xor_b32_e32 v6, 8, v4
	v_cmp_lt_i32_e32 vcc, v6, v8
	v_cmp_gt_u32_e64 s[38:39], 32, v2
	s_mov_b64 s[26:27], 0
	v_cndmask_b32_e32 v6, v4, v6, vcc
	v_lshlrev_b32_e32 v17, 2, v6
	v_and_b32_e32 v6, 4, v34
	v_cmp_eq_u32_e64 s[44:45], 0, v6
	v_xor_b32_e32 v6, 4, v4
	v_cmp_lt_i32_e32 vcc, v6, v8
	v_lshlrev_b32_e32 v21, 2, v2
	s_nop 0
	v_cndmask_b32_e32 v6, v4, v6, vcc
	v_lshlrev_b32_e32 v18, 2, v6
	v_xor_b32_e32 v6, 1, v4
	v_cmp_lt_i32_e32 vcc, v6, v8
	s_nop 1
	v_cndmask_b32_e32 v6, v4, v6, vcc
	v_lshlrev_b32_e32 v19, 2, v6
	v_xor_b32_e32 v6, 2, v4
	v_cmp_lt_i32_e32 vcc, v6, v8
	s_nop 1
	v_cndmask_b32_e32 v4, v4, v6, vcc
	v_lshlrev_b32_e32 v20, 2, v4
	v_and_b32_e32 v4, 3, v34
	v_cmp_eq_u32_e64 s[46:47], 0, v4
	v_bfe_u32 v6, v34, 2, 4
	s_branch .LBB0_538
.LBB0_537:
	s_or_b64 exec, exec, s[28:29]
	v_add_u32_e32 v3, s65, v3
	s_movk_i32 s4, 0xfff
	v_cmp_lt_i32_e32 vcc, s4, v3
	s_or_b64 s[26:27], vcc, s[26:27]
	s_andn2_b64 exec, exec, s[26:27]
	s_cbranch_execz .LBB0_540

.LBB0_540:
	s_or_b64 exec, exec, s[0:1]
	s_mov_b64 s[0:1], exec
	v_mov_b32_e32 v2, v0
	s_mul_i32 s4, s54, 3
	s_mov_b32 s5, 0xaaaaaaab
	s_mov_b32 s6, 0x60000
	s_movk_i32 s7, 0x6000
.Lcp_loop:
	v_add_u32_e32 v3, s54, v2
	v_add_u32_e32 v4, s54, v3
	v_mul_hi_u32 v5, v2, s5
	v_lshrrev_b32_e32 v5, 11, v5
	v_lshrrev_b32_e32 v8, 10, v2
	v_mul_u32_u24_e32 v11, 3, v5
	v_sub_u32_e32 v8, v8, v11
	v_and_b32_e32 v11, 0x3ff, v2
	v_cmp_gt_u32_e64 s[38:39], s6, v2
	v_cmp_eq_u32_e64 s[44:45], 2, v8
	v_cmp_gt_u32_e64 s[2:3], s7, v2
	v_lshlrev_b32_e32 v14, 2, v2
	v_add_u32_e32 v14, 0x1000, v14
	v_mul_u32_u24_e32 v36, 0x1c00, v5
	v_lshl_add_u32 v36, v11, 1, v36
	v_add_u32_e32 v36, 0x70e0000, v36
	s_and_b64 s[44:45], s[44:45], s[38:39]
	v_cndmask_b32_e64 v14, v14, v36, s[44:45]
	v_mul_u32_u24_e32 v26, 0xc00, v5
	v_add_lshl_u32 v26, v26, v2, 2
	v_add_u32_e32 v17, 0x3000, v26
	v_add_u32_e32 v26, 0x44f0000, v26
	v_lshlrev_b32_e32 v23, 2, v2
	v_add_u32_e32 v23, 0x40f0000, v23
	v_mul_u32_u24_e32 v20, 0x810, v5
	v_add_u32_e32 v20, v20, v8
	v_add_u32_e32 v20, 0x80d, v20
	v_mul_u32_u24_e32 v20, 0x1c00, v20
	v_lshl_add_u32 v20, v11, 1, v20
	v_lshlrev_b32_e32 v29, 2, v2
	v_add_u32_e32 v29, 0x4080000, v29
	v_mul_hi_u32 v6, v3, s5
	v_lshrrev_b32_e32 v6, 11, v6
	v_lshrrev_b32_e32 v9, 10, v3
	v_mul_u32_u24_e32 v12, 3, v6
	v_sub_u32_e32 v9, v9, v12
	v_and_b32_e32 v12, 0x3ff, v3
	v_cmp_gt_u32_e64 s[40:41], s6, v3
	v_cmp_eq_u32_e64 s[46:47], 2, v9
	v_cmp_gt_u32_e64 s[28:29], s7, v3
	v_lshlrev_b32_e32 v15, 2, v3
	v_add_u32_e32 v15, 0x1000, v15
	v_mul_u32_u24_e32 v37, 0x1c00, v6
	v_lshl_add_u32 v37, v12, 1, v37
	v_add_u32_e32 v37, 0x70e0000, v37
	s_and_b64 s[46:47], s[46:47], s[40:41]
	v_cndmask_b32_e64 v15, v15, v37, s[46:47]
	v_mul_u32_u24_e32 v27, 0xc00, v6
	v_add_lshl_u32 v27, v27, v3, 2
	v_add_u32_e32 v18, 0x3000, v27
	v_add_u32_e32 v27, 0x44f0000, v27
	v_lshlrev_b32_e32 v24, 2, v3
	v_add_u32_e32 v24, 0x40f0000, v24
	v_mul_u32_u24_e32 v21, 0x810, v6
	v_add_u32_e32 v21, v21, v9
	v_add_u32_e32 v21, 0x80d, v21
	v_mul_u32_u24_e32 v21, 0x1c00, v21
	v_lshl_add_u32 v21, v12, 1, v21
	v_lshlrev_b32_e32 v30, 2, v3
	v_add_u32_e32 v30, 0x4080000, v30
	v_mul_hi_u32 v7, v4, s5
	v_lshrrev_b32_e32 v7, 11, v7
	v_lshrrev_b32_e32 v10, 10, v4
	v_mul_u32_u24_e32 v13, 3, v7
	v_sub_u32_e32 v10, v10, v13
	v_and_b32_e32 v13, 0x3ff, v4
	v_cmp_gt_u32_e64 s[42:43], s6, v4
	v_cmp_eq_u32_e64 s[10:11], 2, v10
	v_cmp_gt_u32_e64 s[74:75], s7, v4
	v_lshlrev_b32_e32 v16, 2, v4
	v_add_u32_e32 v16, 0x1000, v16
	v_mul_u32_u24_e32 v38, 0x1c00, v7
	v_lshl_add_u32 v38, v13, 1, v38
	v_add_u32_e32 v38, 0x70e0000, v38
	s_and_b64 s[10:11], s[10:11], s[42:43]
	v_cndmask_b32_e64 v16, v16, v38, s[10:11]
	v_mul_u32_u24_e32 v28, 0xc00, v7
	v_add_lshl_u32 v28, v28, v4, 2
	v_add_u32_e32 v19, 0x3000, v28
	v_add_u32_e32 v28, 0x44f0000, v28
	v_lshlrev_b32_e32 v25, 2, v4
	v_add_u32_e32 v25, 0x40f0000, v25
	v_mul_u32_u24_e32 v22, 0x810, v7
	v_add_u32_e32 v22, v22, v10
	v_add_u32_e32 v22, 0x80d, v22
	v_mul_u32_u24_e32 v22, 0x1c00, v22
	v_lshl_add_u32 v22, v13, 1, v22
	v_lshlrev_b32_e32 v31, 2, v4
	v_add_u32_e32 v31, 0x4080000, v31
	s_andn2_b64 exec, s[38:39], s[44:45]
	global_load_dword v36, v14, s[72:73]
	s_mov_b64 exec, s[44:45]
	global_load_ushort v36, v14, s[56:57]
	s_mov_b64 exec, s[38:39]
	global_load_dword v39, v17, s[80:81]
	s_mov_b64 exec, s[2:3]
	global_load_ushort v42, v20, s[56:57]
	s_andn2_b64 exec, s[40:41], s[46:47]
	global_load_dword v37, v15, s[72:73]
	s_mov_b64 exec, s[46:47]
	global_load_ushort v37, v15, s[56:57]
	s_mov_b64 exec, s[40:41]
	global_load_dword v40, v18, s[80:81]
	s_mov_b64 exec, s[28:29]
	global_load_ushort v43, v21, s[56:57]
	s_andn2_b64 exec, s[42:43], s[10:11]
	global_load_dword v38, v16, s[72:73]
	s_mov_b64 exec, s[10:11]
	global_load_ushort v38, v16, s[56:57]
	s_mov_b64 exec, s[42:43]
	global_load_dword v41, v19, s[80:81]
	s_mov_b64 exec, s[74:75]
	global_load_ushort v44, v22, s[56:57]
	s_mov_b64 exec, s[0:1]
	s_waitcnt vmcnt(0)
	s_mov_b64 exec, s[44:45]
	v_lshlrev_b32_e32 v36, 16, v36
	s_mov_b64 exec, s[38:39]
	global_store_dword v23, v36, s[90:91]
	global_store_dword v26, v39, s[90:91]
	s_mov_b64 exec, s[2:3]
	v_lshlrev_b32_e32 v42, 16, v42
	global_store_dword v29, v42, s[90:91]
	s_mov_b64 exec, s[46:47]
	v_lshlrev_b32_e32 v37, 16, v37
	s_mov_b64 exec, s[40:41]
	global_store_dword v24, v37, s[90:91]
	global_store_dword v27, v40, s[90:91]
	s_mov_b64 exec, s[28:29]
	v_lshlrev_b32_e32 v43, 16, v43
	global_store_dword v30, v43, s[90:91]
	s_mov_b64 exec, s[10:11]
	v_lshlrev_b32_e32 v38, 16, v38
	s_mov_b64 exec, s[42:43]
	global_store_dword v25, v38, s[90:91]
	global_store_dword v28, v41, s[90:91]
	s_mov_b64 exec, s[74:75]
	v_lshlrev_b32_e32 v44, 16, v44
	global_store_dword v31, v44, s[90:91]
	s_mov_b64 exec, s[0:1]
	v_add_u32_e32 v2, s4, v2
	v_cmp_gt_u32_e32 vcc, s6, v2
	s_cbranch_vccnz .Lcp_loop

.LBB0_869:
	v_lshl_add_u64 v[22:23], s[92:93], 0, v[14:15]
	v_lshl_add_u64 v[24:25], s[92:93], 0, v[16:17]
	v_add_co_u32_e32 v0, vcc, 0x7380000, v22
	s_nop 1
	v_addc_co_u32_e32 v1, vcc, 0, v23, vcc
	v_add_co_u32_e32 v2, vcc, 0x7480000, v22
	s_nop 1
	v_addc_co_u32_e32 v3, vcc, 0, v23, vcc
	v_add_co_u32_e32 v4, vcc, 0x7580000, v22
	s_nop 1
	v_addc_co_u32_e32 v5, vcc, 0, v23, vcc
	v_add_co_u32_e32 v6, vcc, 0x7680000, v22
	s_nop 1
	v_addc_co_u32_e32 v7, vcc, 0, v23, vcc
	v_add_co_u32_e32 v18, vcc, 0x1200000, v24
	s_nop 1
	v_addc_co_u32_e32 v19, vcc, 0, v25, vcc
	global_load_dwordx4 v[76:79], v[0:1], off
	global_load_dwordx4 v[92:95], v[2:3], off
	global_load_dwordx4 v[108:111], v[4:5], off
	global_load_dwordx4 v[124:127], v[6:7], off
	global_load_dwordx2 v[140:141], v[18:19], off
	global_load_dwordx4 v[148:151], v[8:9], off
	global_load_dwordx4 v[80:83], v[0:1], off offset:1024
	global_load_dwordx4 v[96:99], v[2:3], off offset:1024
	global_load_dwordx4 v[112:115], v[4:5], off offset:1024
	global_load_dwordx4 v[128:131], v[6:7], off offset:1024
	global_load_dwordx2 v[142:143], v[18:19], off offset:512
	global_load_dwordx4 v[152:155], v[8:9], off offset:1024
	global_load_dwordx4 v[84:87], v[0:1], off offset:2048
	global_load_dwordx4 v[100:103], v[2:3], off offset:2048
	global_load_dwordx4 v[116:119], v[4:5], off offset:2048
	global_load_dwordx4 v[132:135], v[6:7], off offset:2048
	global_load_dwordx2 v[144:145], v[18:19], off offset:1024
	global_load_dwordx4 v[156:159], v[8:9], off offset:2048
	global_load_dwordx4 v[88:91], v[0:1], off offset:3072
	global_load_dwordx4 v[104:107], v[2:3], off offset:3072
	global_load_dwordx4 v[120:123], v[4:5], off offset:3072
	global_load_dwordx4 v[136:139], v[6:7], off offset:3072
	global_load_dwordx2 v[146:147], v[18:19], off offset:1536
	global_load_dwordx4 v[160:163], v[8:9], off offset:3072
	s_mov_b32 s0, 0xf800000
	v_add_u32_e32 v48, s64, v48
	v_lshl_add_u64 v[14:15], v[14:15], 0, s[20:21]
	v_lshl_add_u64 v[16:17], v[16:17], 0, s[22:23]
	v_mov_b32_e32 v0, 0
	s_waitcnt vmcnt(18)
	v_pk_add_f32 v[76:77], v[76:77], v[92:93]
	v_pk_add_f32 v[78:79], v[78:79], v[94:95]
	v_pk_add_f32 v[76:77], v[76:77], v[108:109]
	v_pk_add_f32 v[78:79], v[78:79], v[110:111]
	v_pk_add_f32 v[76:77], v[76:77], v[124:125]
	v_pk_add_f32 v[78:79], v[78:79], v[126:127]
	v_lshlrev_b32_e32 v164, 16, v140
	v_and_b32_e32 v165, 0xffff0000, v140
	v_lshlrev_b32_e32 v166, 16, v141
	v_and_b32_e32 v167, 0xffff0000, v141
	v_pk_fma_f32 v[148:149], v[164:165], s[28:29], v[148:149] op_sel_hi:[1,0,1]
	v_pk_fma_f32 v[150:151], v[166:167], s[28:29], v[150:151] op_sel_hi:[1,0,1]
	v_pk_add_f32 v[20:21], v[76:77], v[148:149]
	v_pk_add_f32 v[22:23], v[78:79], v[150:151]
	v_add_f32_e32 v164, v20, v21
	v_add_f32_e32 v165, v22, v23
	v_add_f32_e32 v164, v164, v165
	v_add_f32_e32 v0, v0, v164
	s_waitcnt vmcnt(12)
	v_pk_add_f32 v[80:81], v[80:81], v[96:97]
	v_pk_add_f32 v[82:83], v[82:83], v[98:99]
	v_pk_add_f32 v[80:81], v[80:81], v[112:113]
	v_pk_add_f32 v[82:83], v[82:83], v[114:115]
	v_pk_add_f32 v[80:81], v[80:81], v[128:129]
	v_pk_add_f32 v[82:83], v[82:83], v[130:131]
	v_lshlrev_b32_e32 v164, 16, v142
	v_and_b32_e32 v165, 0xffff0000, v142
	v_lshlrev_b32_e32 v166, 16, v143
	v_and_b32_e32 v167, 0xffff0000, v143
	v_pk_fma_f32 v[152:153], v[164:165], s[28:29], v[152:153] op_sel_hi:[1,0,1]
	v_pk_fma_f32 v[154:155], v[166:167], s[28:29], v[154:155] op_sel_hi:[1,0,1]
	v_pk_add_f32 v[24:25], v[80:81], v[152:153]
	v_pk_add_f32 v[26:27], v[82:83], v[154:155]
	v_add_f32_e32 v164, v24, v25
	v_add_f32_e32 v165, v26, v27
	v_add_f32_e32 v164, v164, v165
	v_add_f32_e32 v0, v0, v164
	s_waitcnt vmcnt(6)
	v_pk_add_f32 v[84:85], v[84:85], v[100:101]
	v_pk_add_f32 v[86:87], v[86:87], v[102:103]
	v_pk_add_f32 v[84:85], v[84:85], v[116:117]
	v_pk_add_f32 v[86:87], v[86:87], v[118:119]
	v_pk_add_f32 v[84:85], v[84:85], v[132:133]
	v_pk_add_f32 v[86:87], v[86:87], v[134:135]
	v_lshlrev_b32_e32 v164, 16, v144
	v_and_b32_e32 v165, 0xffff0000, v144
	v_lshlrev_b32_e32 v166, 16, v145
	v_and_b32_e32 v167, 0xffff0000, v145
	v_pk_fma_f32 v[156:157], v[164:165], s[28:29], v[156:157] op_sel_hi:[1,0,1]
	v_pk_fma_f32 v[158:159], v[166:167], s[28:29], v[158:159] op_sel_hi:[1,0,1]
	v_pk_add_f32 v[28:29], v[84:85], v[156:157]
	v_pk_add_f32 v[30:31], v[86:87], v[158:159]
	v_add_f32_e32 v164, v28, v29
	v_add_f32_e32 v165, v30, v31
	v_add_f32_e32 v164, v164, v165
	v_add_f32_e32 v0, v0, v164
	s_waitcnt vmcnt(0)
	v_pk_add_f32 v[88:89], v[88:89], v[104:105]
	v_pk_add_f32 v[90:91], v[90:91], v[106:107]
	v_pk_add_f32 v[88:89], v[88:89], v[120:121]
	v_pk_add_f32 v[90:91], v[90:91], v[122:123]
	v_pk_add_f32 v[88:89], v[88:89], v[136:137]
	v_pk_add_f32 v[90:91], v[90:91], v[138:139]
	v_lshlrev_b32_e32 v164, 16, v146
	v_and_b32_e32 v165, 0xffff0000, v146
	v_lshlrev_b32_e32 v166, 16, v147
	v_and_b32_e32 v167, 0xffff0000, v147
	v_pk_fma_f32 v[160:161], v[164:165], s[28:29], v[160:161] op_sel_hi:[1,0,1]
	v_pk_fma_f32 v[162:163], v[166:167], s[28:29], v[162:163] op_sel_hi:[1,0,1]
	v_pk_add_f32 v[32:33], v[88:89], v[160:161]
	v_pk_add_f32 v[34:35], v[90:91], v[162:163]
	v_add_f32_e32 v164, v32, v33
	v_add_f32_e32 v165, v34, v35
	v_add_f32_e32 v164, v164, v165
	v_add_f32_e32 v0, v0, v164
	ds_bpermute_b32 v1, v40, v0
	s_waitcnt lgkmcnt(0)
	v_add_f32_e32 v0, v0, v1
	ds_bpermute_b32 v1, v41, v0
	s_waitcnt lgkmcnt(0)
	v_add_f32_e32 v0, v0, v1
	ds_bpermute_b32 v1, v42, v0
	s_waitcnt lgkmcnt(0)
	v_add_f32_e32 v0, v0, v1
	ds_bpermute_b32 v1, v43, v0
	s_waitcnt lgkmcnt(0)
	v_add_f32_e32 v0, v0, v1
	ds_bpermute_b32 v1, v44, v0
	s_waitcnt lgkmcnt(0)
	v_add_f32_e32 v0, v0, v1
	ds_bpermute_b32 v1, v45, v0
	s_waitcnt lgkmcnt(0)
	v_add_f32_e32 v36, v0, v1
	v_fmamk_f32 v21, v36, 0xba800000, v21
	v_fmac_f32_e32 v20, 0xba800000, v36
	v_fmamk_f32 v23, v36, 0xba800000, v23
	v_fmac_f32_e32 v22, 0xba800000, v36
	v_pk_mul_f32 v[0:1], v[22:23], v[22:23]
	v_pk_mul_f32 v[2:3], v[20:21], v[20:21]
	v_fmamk_f32 v25, v36, 0xba800000, v25
	v_pk_mov_b32 v[4:5], v[2:3], v[0:1] op_sel:[1,0]
	v_mov_b32_e32 v3, v1
	v_pk_add_f32 v[0:1], v[4:5], v[2:3]
	v_fmac_f32_e32 v24, 0xba800000, v36
	v_fmamk_f32 v27, v36, 0xba800000, v27
	v_fmac_f32_e32 v26, 0xba800000, v36
	v_pk_add_f32 v[0:1], v[0:1], v[0:1] op_sel_hi:[0,1]
	v_pk_mul_f32 v[2:3], v[26:27], v[26:27]
	v_pk_mul_f32 v[4:5], v[24:25], v[24:25]
	v_fmac_f32_e32 v28, 0xba800000, v36
	v_pk_mov_b32 v[6:7], v[4:5], v[2:3] op_sel:[1,0]
	v_mov_b32_e32 v5, v3
	v_fmamk_f32 v29, v36, 0xba800000, v29
	v_fmac_f32_e32 v30, 0xba800000, v36
	v_mul_f32_e32 v0, v28, v28
	v_pk_add_f32 v[2:3], v[6:7], v[4:5]
	v_fmamk_f32 v31, v36, 0xba800000, v31
	v_pk_fma_f32 v[4:5], v[28:29], v[28:29], v[0:1] op_sel_hi:[1,1,0]
	v_mul_f32_e32 v0, v30, v30
	v_pk_add_f32 v[2:3], v[2:3], v[2:3] op_sel_hi:[0,1]
	v_pk_fma_f32 v[6:7], v[30:31], v[30:31], v[0:1] op_sel_hi:[1,1,0]
	v_fmamk_f32 v35, v36, 0xba800000, v35
	v_fmac_f32_e32 v34, 0xba800000, v36
	v_fmamk_f32 v33, v36, 0xba800000, v33
	v_fmac_f32_e32 v32, 0xba800000, v36
	v_mul_f32_e32 v4, v32, v32
	v_mul_f32_e32 v6, v33, v33
	v_mul_f32_e32 v0, v34, v34
	v_mul_f32_e32 v2, v35, v35
	v_pk_add_f32 v[4:5], v[4:5], v[6:7]
	v_pk_add_f32 v[0:1], v[0:1], v[2:3]
	s_nop 0
	v_pk_add_f32 v[0:1], v[4:5], v[0:1]
	s_nop 0
	v_add_f32_e32 v0, v0, v1
	ds_bpermute_b32 v1, v40, v0
	s_waitcnt lgkmcnt(0)
	v_add_f32_e32 v0, v0, v1
	ds_bpermute_b32 v1, v41, v0
	s_waitcnt lgkmcnt(0)
	v_add_f32_e32 v0, v0, v1
	ds_bpermute_b32 v1, v42, v0
	s_waitcnt lgkmcnt(0)
	v_add_f32_e32 v0, v0, v1
	ds_bpermute_b32 v1, v43, v0
	s_waitcnt lgkmcnt(0)
	v_add_f32_e32 v0, v0, v1
	ds_bpermute_b32 v1, v44, v0
	s_waitcnt lgkmcnt(0)
	v_add_f32_e32 v0, v0, v1
	ds_bpermute_b32 v1, v45, v0
	s_waitcnt lgkmcnt(0)
	v_add_f32_e32 v0, v0, v1
	v_fmamk_f32 v0, v0, 0x3a800000, v46
	v_cmp_gt_f32_e32 vcc, s0, v0
	v_mul_f32_e32 v1, 0x4f800000, v0
	s_nop 0
	v_cndmask_b32_e32 v0, v0, v1, vcc
	v_sqrt_f32_e32 v1, v0
	s_nop 0
	v_add_u32_e32 v2, -1, v1
	v_fma_f32 v3, -v2, v1, v0
	v_cmp_ge_f32_e64 s[0:1], 0, v3
	v_add_u32_e32 v3, 1, v1
	s_nop 0
	v_cndmask_b32_e64 v2, v1, v2, s[0:1]
	v_fma_f32 v1, -v3, v1, v0
	v_cmp_lt_f32_e64 s[0:1], 0, v1
	s_nop 1
	v_cndmask_b32_e64 v1, v2, v3, s[0:1]
	v_mul_f32_e32 v2, 0x37800000, v1
	v_cndmask_b32_e32 v1, v1, v2, vcc
	v_cmp_class_f32_e32 vcc, v0, v47
	s_nop 1
	v_cndmask_b32_e32 v0, v1, v0, vcc
	v_div_scale_f32 v1, s[0:1], v0, v0, 1.0
	v_rcp_f32_e32 v2, v1
	s_movk_i32 s0, 0x40ff
	v_fma_f32 v3, -v1, v2, 1.0
	v_fmac_f32_e32 v2, v3, v2
	v_div_scale_f32 v3, vcc, 1.0, v0, 1.0
	v_mul_f32_e32 v4, v3, v2
	v_fma_f32 v5, -v1, v4, v3
	v_fmac_f32_e32 v4, v5, v2
	v_fma_f32 v1, -v1, v4, v3
	v_div_fmas_f32 v1, v1, v2, v4
	v_div_fixup_f32 v36, v1, v0, 1.0
	global_load_dwordx4 v[0:3], v[10:11], off
	global_load_dwordx4 v[4:7], v[12:13], off
	v_pk_mul_f32 v[20:21], v[20:21], v[36:37] op_sel_hi:[1,0]
	v_pk_mul_f32 v[22:23], v[22:23], v[36:37] op_sel_hi:[1,0]
	v_cmp_lt_i32_e32 vcc, s0, v48
	s_or_b64 s[26:27], vcc, s[26:27]
	s_waitcnt vmcnt(0)
	v_pk_fma_f32 v[0:1], v[0:1], v[20:21], v[4:5]
	v_pk_fma_f32 v[2:3], v[2:3], v[22:23], v[6:7]
	v_cvt_pk_bf16_f32 v0, v0, v1
	v_pk_mul_f32 v[20:21], v[24:25], v[36:37] op_sel_hi:[1,0]
	v_cvt_pk_bf16_f32 v1, v2, v3
	global_store_dwordx2 v[18:19], v[0:1], off
	global_load_dwordx4 v[0:3], v[10:11], off offset:1024
	s_nop 0
	global_load_dwordx4 v[4:7], v[12:13], off offset:1024
	v_pk_mul_f32 v[22:23], v[26:27], v[36:37] op_sel_hi:[1,0]
	s_waitcnt vmcnt(0)
	v_pk_fma_f32 v[0:1], v[0:1], v[20:21], v[4:5]
	v_pk_fma_f32 v[2:3], v[2:3], v[22:23], v[6:7]
	v_cvt_pk_bf16_f32 v0, v0, v1
	v_pk_mul_f32 v[20:21], v[28:29], v[36:37] op_sel_hi:[1,0]
	v_cvt_pk_bf16_f32 v1, v2, v3
	global_store_dwordx2 v[18:19], v[0:1], off offset:512
	global_load_dwordx4 v[0:3], v[10:11], off offset:2048
	s_nop 0
	global_load_dwordx4 v[4:7], v[12:13], off offset:2048
	v_pk_mul_f32 v[22:23], v[30:31], v[36:37] op_sel_hi:[1,0]
	s_waitcnt vmcnt(0)
	v_pk_fma_f32 v[0:1], v[0:1], v[20:21], v[4:5]
	v_pk_fma_f32 v[2:3], v[2:3], v[22:23], v[6:7]
	v_cvt_pk_bf16_f32 v0, v0, v1
	v_pk_mul_f32 v[20:21], v[32:33], v[36:37] op_sel_hi:[1,0]
	v_cvt_pk_bf16_f32 v1, v2, v3
	global_store_dwordx2 v[18:19], v[0:1], off offset:1024
	global_load_dwordx4 v[0:3], v[10:11], off offset:3072
	s_nop 0
	global_load_dwordx4 v[4:7], v[12:13], off offset:3072
	v_pk_mul_f32 v[22:23], v[34:35], v[36:37] op_sel_hi:[1,0]
	s_waitcnt vmcnt(0)
	v_pk_fma_f32 v[0:1], v[0:1], v[20:21], v[4:5]
	v_pk_fma_f32 v[2:3], v[2:3], v[22:23], v[6:7]
	v_cvt_pk_bf16_f32 v0, v0, v1
	s_nop 0
	v_cvt_pk_bf16_f32 v1, v2, v3
	global_store_dwordx2 v[18:19], v[0:1], off offset:1536
	s_andn2_b64 exec, exec, s[26:27]
	s_cbranch_execnz .LBB0_869
